# GEMM loops: the s_setprio 1 / s_setprio 0 flips moved across the phase barriers so an MMA segment is barrier, 32 MFMAs, barrier with nothing else in it
# speedup vs baseline: 1.0075x; 1.0007x over previous
.LBB0_176:
	s_add_u32 s2, s14, 0xfffc0080
	s_addc_u32 s3, s15, -1
	s_add_i32 s47, 0, 0x10000
	s_cmp_eq_u32 s46, 12
	s_cselect_b32 s25, s7, s3
	s_cselect_b32 s24, s11, s2
	v_add_u32_e32 v0, s47, v155
	s_cselect_b32 s3, s13, s33
	s_cselect_b32 s2, s29, s31
	s_add_i32 s54, 0, 0x14000
	ds_read_b128 v[50:53], v0
	ds_read_b128 v[54:57], v0 offset:1024
	ds_read_b128 v[58:61], v0 offset:2048
	ds_read_b128 v[62:65], v0 offset:3072
	v_add_u32_e32 v0, s54, v155
	ds_read_b128 v[176:179], v0
	ds_read_b128 v[188:191], v0 offset:1024
	ds_read_b128 v[192:195], v0 offset:2048
	ds_read_b128 v[196:199], v0 offset:3072
	v_lshl_add_u64 v[180:181], s[14:15], 0, v[170:171]
	s_add_i32 m0, s90, 0xc000
	ds_read_b128 v[200:203], v186
	ds_read_b128 v[204:207], v186 offset:1024
	ds_read_b128 v[226:229], v186 offset:2048
	ds_read_b128 v[230:233], v186 offset:3072
	ds_read_b128 v[234:237], v186 offset:4096
	ds_read_b128 v[238:241], v186 offset:5120
	ds_read_b128 v[242:245], v186 offset:6144
	ds_read_b128 v[246:249], v186 offset:7168
	global_load_lds_dwordx4 v[180:181], off
	v_lshl_add_u64 v[180:181], s[14:15], 0, v[172:173]
	s_add_i32 m0, s90, 0xe000
	s_nop 0
	global_load_lds_dwordx4 v[180:181], off
	s_waitcnt vmcnt(8)
	s_waitcnt lgkmcnt(0)
	s_setprio 1
	s_barrier
	s_waitcnt lgkmcnt(0)
	v_mfma_f32_16x16x32_bf16 v[142:145], v[50:53], v[200:203], v[142:145]
	v_mfma_f32_16x16x32_bf16 v[138:141], v[58:61], v[200:203], v[138:141]
	v_mfma_f32_16x16x32_bf16 v[126:129], v[50:53], v[226:229], v[126:129]
	v_mfma_f32_16x16x32_bf16 v[122:125], v[58:61], v[226:229], v[122:125]
	v_mfma_f32_16x16x32_bf16 v[110:113], v[50:53], v[234:237], v[110:113]
	v_mfma_f32_16x16x32_bf16 v[106:109], v[58:61], v[234:237], v[106:109]
	v_mfma_f32_16x16x32_bf16 v[94:97], v[50:53], v[242:245], v[94:97]
	v_mfma_f32_16x16x32_bf16 v[90:93], v[58:61], v[242:245], v[90:93]
	v_mfma_f32_16x16x32_bf16 v[142:145], v[54:57], v[204:207], v[142:145]
	v_mfma_f32_16x16x32_bf16 v[138:141], v[62:65], v[204:207], v[138:141]
	v_mfma_f32_16x16x32_bf16 v[126:129], v[54:57], v[230:233], v[126:129]
	v_mfma_f32_16x16x32_bf16 v[122:125], v[62:65], v[230:233], v[122:125]
	v_mfma_f32_16x16x32_bf16 v[110:113], v[54:57], v[238:241], v[110:113]
	v_mfma_f32_16x16x32_bf16 v[106:109], v[62:65], v[238:241], v[106:109]
	v_mfma_f32_16x16x32_bf16 v[94:97], v[54:57], v[246:249], v[94:97]
	v_mfma_f32_16x16x32_bf16 v[90:93], v[62:65], v[246:249], v[90:93]
	s_setprio 0
	s_setprio 1
	v_mfma_f32_16x16x32_bf16 v[134:137], v[176:179], v[200:203], v[134:137]
	v_mfma_f32_16x16x32_bf16 v[130:133], v[192:195], v[200:203], v[130:133]
	v_mfma_f32_16x16x32_bf16 v[118:121], v[176:179], v[226:229], v[118:121]
	v_mfma_f32_16x16x32_bf16 v[114:117], v[192:195], v[226:229], v[114:117]
	v_mfma_f32_16x16x32_bf16 v[102:105], v[176:179], v[234:237], v[102:105]
	v_mfma_f32_16x16x32_bf16 v[98:101], v[192:195], v[234:237], v[98:101]
	v_mfma_f32_16x16x32_bf16 v[86:89], v[176:179], v[242:245], v[86:89]
	v_mfma_f32_16x16x32_bf16 v[82:85], v[192:195], v[242:245], v[82:85]
	v_mfma_f32_16x16x32_bf16 v[134:137], v[188:191], v[204:207], v[134:137]
	v_mfma_f32_16x16x32_bf16 v[130:133], v[196:199], v[204:207], v[130:133]
	v_mfma_f32_16x16x32_bf16 v[118:121], v[188:191], v[230:233], v[118:121]
	v_mfma_f32_16x16x32_bf16 v[114:117], v[196:199], v[230:233], v[114:117]
	v_mfma_f32_16x16x32_bf16 v[102:105], v[188:191], v[238:241], v[102:105]
	v_mfma_f32_16x16x32_bf16 v[98:101], v[196:199], v[238:241], v[98:101]
	v_mfma_f32_16x16x32_bf16 v[86:89], v[188:191], v[246:249], v[86:89]
	v_mfma_f32_16x16x32_bf16 v[82:85], v[196:199], v[246:249], v[82:85]
	s_barrier
	s_setprio 0
	s_add_i32 s47, s47, s42
	v_lshl_add_u64 v[180:181], s[2:3], 0, v[146:147]
	s_mov_b32 m0, s47
	ds_read_b128 v[200:203], v186 offset:16384
	ds_read_b128 v[204:207], v186 offset:17408
	ds_read_b128 v[226:229], v186 offset:18432
	ds_read_b128 v[230:233], v186 offset:19456
	ds_read_b128 v[234:237], v186 offset:20480
	ds_read_b128 v[238:241], v186 offset:21504
	ds_read_b128 v[242:245], v186 offset:22528
	ds_read_b128 v[246:249], v186 offset:23552
	global_load_lds_dwordx4 v[180:181], off
	s_add_i32 m0, s47, 0x2000
	s_add_u32 s58, s2, 0x40000
	v_lshl_add_u64 v[222:223], s[2:3], 0, v[148:149]
	s_addc_u32 s59, s3, 0
	s_add_i32 s47, s54, s42
	global_load_lds_dwordx4 v[222:223], off
	v_lshl_add_u64 v[224:225], s[58:59], 0, v[146:147]
	s_mov_b32 m0, s47
	v_lshl_add_u64 v[250:251], s[24:25], 0, v[148:149]
	global_load_lds_dwordx4 v[224:225], off
	v_lshl_add_u64 v[224:225], s[58:59], 0, v[148:149]
	s_add_i32 m0, s47, 0x2000
	s_nop 0
	global_load_lds_dwordx4 v[224:225], off
	v_lshl_add_u64 v[224:225], s[24:25], 0, v[146:147]
	s_mov_b32 m0, s90
	s_nop 0
	global_load_lds_dwordx4 v[224:225], off
	s_mov_b32 m0, s91
	s_nop 0
	global_load_lds_dwordx4 v[250:251], off
	s_waitcnt vmcnt(8)
	s_waitcnt lgkmcnt(0)
	s_setprio 1
	s_barrier
	s_waitcnt lgkmcnt(0)
	v_mfma_f32_16x16x32_bf16 v[78:81], v[50:53], v[200:203], v[78:81]
	v_mfma_f32_16x16x32_bf16 v[74:77], v[58:61], v[200:203], v[74:77]
	v_mfma_f32_16x16x32_bf16 v[46:49], v[50:53], v[226:229], v[46:49]
	v_mfma_f32_16x16x32_bf16 v[42:45], v[58:61], v[226:229], v[42:45]
	v_mfma_f32_16x16x32_bf16 v[30:33], v[50:53], v[234:237], v[30:33]
	v_mfma_f32_16x16x32_bf16 v[26:29], v[58:61], v[234:237], v[26:29]
	v_mfma_f32_16x16x32_bf16 v[14:17], v[50:53], v[242:245], v[14:17]
	v_mfma_f32_16x16x32_bf16 v[10:13], v[58:61], v[242:245], v[10:13]
	v_mfma_f32_16x16x32_bf16 v[78:81], v[54:57], v[204:207], v[78:81]
	v_mfma_f32_16x16x32_bf16 v[74:77], v[62:65], v[204:207], v[74:77]
	v_mfma_f32_16x16x32_bf16 v[46:49], v[54:57], v[230:233], v[46:49]
	v_mfma_f32_16x16x32_bf16 v[42:45], v[62:65], v[230:233], v[42:45]
	v_mfma_f32_16x16x32_bf16 v[30:33], v[54:57], v[238:241], v[30:33]
	v_mfma_f32_16x16x32_bf16 v[26:29], v[62:65], v[238:241], v[26:29]
	v_mfma_f32_16x16x32_bf16 v[14:17], v[54:57], v[246:249], v[14:17]
	v_mfma_f32_16x16x32_bf16 v[10:13], v[62:65], v[246:249], v[10:13]
	s_setprio 0
	s_setprio 1
	v_mfma_f32_16x16x32_bf16 v[38:41], v[176:179], v[226:229], v[38:41]
	v_mfma_f32_16x16x32_bf16 v[34:37], v[192:195], v[226:229], v[34:37]
	v_mfma_f32_16x16x32_bf16 v[22:25], v[176:179], v[234:237], v[22:25]
	v_mfma_f32_16x16x32_bf16 v[18:21], v[192:195], v[234:237], v[18:21]
	v_mfma_f32_16x16x32_bf16 v[6:9], v[176:179], v[242:245], v[6:9]
	v_mfma_f32_16x16x32_bf16 v[2:5], v[192:195], v[242:245], v[2:5]
	v_mfma_f32_16x16x32_bf16 v[50:53], v[176:179], v[200:203], v[70:73]
	v_mfma_f32_16x16x32_bf16 v[54:57], v[192:195], v[200:203], v[66:69]
	v_mfma_f32_16x16x32_bf16 v[38:41], v[188:191], v[230:233], v[38:41]
	v_mfma_f32_16x16x32_bf16 v[34:37], v[196:199], v[230:233], v[34:37]
	v_mfma_f32_16x16x32_bf16 v[22:25], v[188:191], v[238:241], v[22:25]
	v_mfma_f32_16x16x32_bf16 v[18:21], v[196:199], v[238:241], v[18:21]
	v_mfma_f32_16x16x32_bf16 v[6:9], v[188:191], v[246:249], v[6:9]
	v_mfma_f32_16x16x32_bf16 v[2:5], v[196:199], v[246:249], v[2:5]
	v_mfma_f32_16x16x32_bf16 v[50:53], v[188:191], v[204:207], v[50:53]
	v_mfma_f32_16x16x32_bf16 v[54:57], v[196:199], v[204:207], v[54:57]
	s_barrier
	s_setprio 0
	s_add_i32 s47, 0, 0x18000
	v_add_u32_e32 v0, s47, v155
	s_add_i32 s54, 0, 0x1c000
	ds_read_b128 v[58:61], v0
	ds_read_b128 v[62:65], v0 offset:1024
	ds_read_b128 v[66:69], v0 offset:2048
	ds_read_b128 v[70:73], v0 offset:3072
	v_add_u32_e32 v0, s54, v155
	ds_read_b128 v[176:179], v0
	ds_read_b128 v[188:191], v0 offset:1024
	ds_read_b128 v[192:195], v0 offset:2048
	ds_read_b128 v[196:199], v0 offset:3072
	s_add_u32 s24, s24, 0x40000
	s_addc_u32 s25, s25, 0
	s_mov_b32 m0, s74
	v_lshl_add_u64 v[218:219], s[24:25], 0, v[146:147]
	ds_read_b128 v[200:203], v186 offset:32768
	ds_read_b128 v[204:207], v186 offset:33792
	ds_read_b128 v[226:229], v186 offset:34816
	ds_read_b128 v[230:233], v186 offset:35840
	ds_read_b128 v[234:237], v186 offset:36864
	ds_read_b128 v[238:241], v186 offset:37888
	ds_read_b128 v[242:245], v186 offset:38912
	ds_read_b128 v[246:249], v186 offset:39936
	global_load_lds_dwordx4 v[218:219], off
	v_lshl_add_u64 v[218:219], s[24:25], 0, v[148:149]
	s_mov_b32 m0, s75
	s_nop 0
	global_load_lds_dwordx4 v[218:219], off
	s_waitcnt vmcnt(8)
	s_waitcnt lgkmcnt(0)
	s_setprio 1
	s_barrier
	s_waitcnt lgkmcnt(0)
	v_mfma_f32_16x16x32_bf16 v[142:145], v[58:61], v[200:203], v[142:145]
	v_mfma_f32_16x16x32_bf16 v[138:141], v[66:69], v[200:203], v[138:141]
	v_mfma_f32_16x16x32_bf16 v[126:129], v[58:61], v[226:229], v[126:129]
	v_mfma_f32_16x16x32_bf16 v[122:125], v[66:69], v[226:229], v[122:125]
	v_mfma_f32_16x16x32_bf16 v[110:113], v[58:61], v[234:237], v[110:113]
	v_mfma_f32_16x16x32_bf16 v[106:109], v[66:69], v[234:237], v[106:109]
	v_mfma_f32_16x16x32_bf16 v[94:97], v[58:61], v[242:245], v[94:97]
	v_mfma_f32_16x16x32_bf16 v[90:93], v[66:69], v[242:245], v[90:93]
	v_mfma_f32_16x16x32_bf16 v[142:145], v[62:65], v[204:207], v[142:145]
	v_mfma_f32_16x16x32_bf16 v[138:141], v[70:73], v[204:207], v[138:141]
	v_mfma_f32_16x16x32_bf16 v[126:129], v[62:65], v[230:233], v[126:129]
	v_mfma_f32_16x16x32_bf16 v[122:125], v[70:73], v[230:233], v[122:125]
	v_mfma_f32_16x16x32_bf16 v[110:113], v[62:65], v[238:241], v[110:113]
	v_mfma_f32_16x16x32_bf16 v[106:109], v[70:73], v[238:241], v[106:109]
	v_mfma_f32_16x16x32_bf16 v[94:97], v[62:65], v[246:249], v[94:97]
	v_mfma_f32_16x16x32_bf16 v[90:93], v[70:73], v[246:249], v[90:93]
	s_setprio 0
	s_setprio 1
	v_mfma_f32_16x16x32_bf16 v[134:137], v[176:179], v[200:203], v[134:137]
	v_mfma_f32_16x16x32_bf16 v[130:133], v[192:195], v[200:203], v[130:133]
	v_mfma_f32_16x16x32_bf16 v[118:121], v[176:179], v[226:229], v[118:121]
	v_mfma_f32_16x16x32_bf16 v[114:117], v[192:195], v[226:229], v[114:117]
	v_mfma_f32_16x16x32_bf16 v[102:105], v[176:179], v[234:237], v[102:105]
	v_mfma_f32_16x16x32_bf16 v[98:101], v[192:195], v[234:237], v[98:101]
	v_mfma_f32_16x16x32_bf16 v[86:89], v[176:179], v[242:245], v[86:89]
	v_mfma_f32_16x16x32_bf16 v[82:85], v[192:195], v[242:245], v[82:85]
	v_mfma_f32_16x16x32_bf16 v[134:137], v[188:191], v[204:207], v[134:137]
	v_mfma_f32_16x16x32_bf16 v[130:133], v[196:199], v[204:207], v[130:133]
	v_mfma_f32_16x16x32_bf16 v[118:121], v[188:191], v[230:233], v[118:121]
	v_mfma_f32_16x16x32_bf16 v[114:117], v[196:199], v[230:233], v[114:117]
	v_mfma_f32_16x16x32_bf16 v[102:105], v[188:191], v[238:241], v[102:105]
	v_mfma_f32_16x16x32_bf16 v[98:101], v[196:199], v[238:241], v[98:101]
	v_mfma_f32_16x16x32_bf16 v[86:89], v[188:191], v[246:249], v[86:89]
	v_mfma_f32_16x16x32_bf16 v[82:85], v[196:199], v[246:249], v[82:85]
	s_barrier
	s_setprio 0
	s_add_i32 s24, s47, s42
	v_lshl_add_u64 v[180:181], v[180:181], 0, s[44:45]
	s_mov_b32 m0, s24
	ds_read_b128 v[200:203], v186 offset:49152
	ds_read_b128 v[204:207], v186 offset:50176
	ds_read_b128 v[226:229], v186 offset:51200
	ds_read_b128 v[230:233], v186 offset:52224
	ds_read_b128 v[234:237], v186 offset:53248
	ds_read_b128 v[238:241], v186 offset:54272
	ds_read_b128 v[242:245], v186 offset:55296
	ds_read_b128 v[246:249], v186 offset:56320
	global_load_lds_dwordx4 v[180:181], off
	s_add_i32 m0, s24, 0x2000
	s_add_u32 s2, s2, 0x40080
	v_lshl_add_u64 v[180:181], v[222:223], 0, s[44:45]
	s_addc_u32 s3, s3, 0
	s_add_i32 s24, s54, s42
	global_load_lds_dwordx4 v[180:181], off
	v_lshl_add_u64 v[180:181], s[2:3], 0, v[146:147]
	s_mov_b32 m0, s24
	s_nop 0
	global_load_lds_dwordx4 v[180:181], off
	v_lshl_add_u64 v[180:181], s[2:3], 0, v[148:149]
	s_add_i32 m0, s24, 0x2000
	s_nop 0
	global_load_lds_dwordx4 v[180:181], off
	v_lshl_add_u64 v[180:181], v[224:225], 0, s[44:45]
	s_mov_b32 m0, s20
	s_nop 0
	global_load_lds_dwordx4 v[180:181], off
	v_lshl_add_u64 v[180:181], v[250:251], 0, s[44:45]
	s_mov_b32 m0, s21
	s_nop 0
	global_load_lds_dwordx4 v[180:181], off
	s_waitcnt vmcnt(8)
	s_waitcnt lgkmcnt(0)
	s_setprio 1
	s_barrier
	s_waitcnt lgkmcnt(0)
	v_mfma_f32_16x16x32_bf16 v[78:81], v[58:61], v[200:203], v[78:81]
	v_mfma_f32_16x16x32_bf16 v[74:77], v[66:69], v[200:203], v[74:77]
	v_mfma_f32_16x16x32_bf16 v[46:49], v[58:61], v[226:229], v[46:49]
	v_mfma_f32_16x16x32_bf16 v[42:45], v[66:69], v[226:229], v[42:45]
	v_mfma_f32_16x16x32_bf16 v[30:33], v[58:61], v[234:237], v[30:33]
	v_mfma_f32_16x16x32_bf16 v[26:29], v[66:69], v[234:237], v[26:29]
	v_mfma_f32_16x16x32_bf16 v[14:17], v[58:61], v[242:245], v[14:17]
	v_mfma_f32_16x16x32_bf16 v[10:13], v[66:69], v[242:245], v[10:13]
	v_mfma_f32_16x16x32_bf16 v[78:81], v[62:65], v[204:207], v[78:81]
	v_mfma_f32_16x16x32_bf16 v[74:77], v[70:73], v[204:207], v[74:77]
	v_mfma_f32_16x16x32_bf16 v[46:49], v[62:65], v[230:233], v[46:49]
	v_mfma_f32_16x16x32_bf16 v[42:45], v[70:73], v[230:233], v[42:45]
	v_mfma_f32_16x16x32_bf16 v[30:33], v[62:65], v[238:241], v[30:33]
	v_mfma_f32_16x16x32_bf16 v[26:29], v[70:73], v[238:241], v[26:29]
	v_mfma_f32_16x16x32_bf16 v[14:17], v[62:65], v[246:249], v[14:17]
	v_mfma_f32_16x16x32_bf16 v[10:13], v[70:73], v[246:249], v[10:13]
	s_setprio 0
	s_setprio 1
	v_mfma_f32_16x16x32_bf16 v[50:53], v[176:179], v[200:203], v[50:53]
	v_mfma_f32_16x16x32_bf16 v[70:73], v[188:191], v[204:207], v[50:53]
	v_mfma_f32_16x16x32_bf16 v[50:53], v[192:195], v[200:203], v[54:57]
	v_mfma_f32_16x16x32_bf16 v[38:41], v[176:179], v[226:229], v[38:41]
	v_mfma_f32_16x16x32_bf16 v[34:37], v[192:195], v[226:229], v[34:37]
	v_mfma_f32_16x16x32_bf16 v[22:25], v[176:179], v[234:237], v[22:25]
	v_mfma_f32_16x16x32_bf16 v[18:21], v[192:195], v[234:237], v[18:21]
	v_mfma_f32_16x16x32_bf16 v[6:9], v[176:179], v[242:245], v[6:9]
	v_mfma_f32_16x16x32_bf16 v[2:5], v[192:195], v[242:245], v[2:5]
	v_mfma_f32_16x16x32_bf16 v[66:69], v[196:199], v[204:207], v[50:53]
	v_mfma_f32_16x16x32_bf16 v[38:41], v[188:191], v[230:233], v[38:41]
	v_mfma_f32_16x16x32_bf16 v[34:37], v[196:199], v[230:233], v[34:37]
	v_mfma_f32_16x16x32_bf16 v[22:25], v[188:191], v[238:241], v[22:25]
	v_mfma_f32_16x16x32_bf16 v[18:21], v[196:199], v[238:241], v[18:21]
	v_mfma_f32_16x16x32_bf16 v[6:9], v[188:191], v[246:249], v[6:9]
	v_mfma_f32_16x16x32_bf16 v[2:5], v[196:199], v[246:249], v[2:5]
	s_barrier
	s_setprio 0
	s_add_i32 s46, s46, 2
	s_add_u32 s14, s14, 0x100
	s_addc_u32 s15, s15, 0
	s_add_u32 s31, s31, 0x100
	s_addc_u32 s33, s33, 0
	s_cmp_gt_u32 s46, 13
	s_cbranch_scc0 .LBB0_176
	s_and_b64 vcc, exec, s[22:23]
	s_cbranch_vccz .LBB0_179
	s_barrier

.LBB0_650:
	s_add_u32 s2, s4, 0x100
	s_addc_u32 s3, s5, 0
	s_add_i32 s49, 0, 0x10000
	s_cmp_eq_u32 s48, 12
	s_cselect_b32 s29, s17, s3
	s_cselect_b32 s28, s25, s2
	v_add_u32_e32 v0, s49, v135
	s_cselect_b32 s27, s15, s47
	s_cselect_b32 s26, s42, s46
	s_add_i32 s50, 0, 0x14000
	ds_read_b128 v[146:149], v0
	ds_read_b128 v[150:153], v0 offset:1024
	ds_read_b128 v[154:157], v0 offset:2048
	ds_read_b128 v[158:161], v0 offset:3072
	v_add_u32_e32 v0, s50, v135
	ds_read_b128 v[162:165], v0
	ds_read_b128 v[166:169], v0 offset:1024
	ds_read_b128 v[170:173], v0 offset:2048
	ds_read_b128 v[174:177], v0 offset:3072
	v_lshl_add_u64 v[142:143], s[4:5], 0, v[138:139]
	s_add_i32 m0, s23, 0xc000
	ds_read_b128 v[178:181], v144
	ds_read_b128 v[182:185], v144 offset:1024
	ds_read_b128 v[186:189], v144 offset:2048
	ds_read_b128 v[190:193], v144 offset:3072
	ds_read_b128 v[194:197], v144 offset:4096
	ds_read_b128 v[198:201], v144 offset:5120
	ds_read_b128 v[202:205], v144 offset:6144
	ds_read_b128 v[222:225], v144 offset:7168
	global_load_lds_dwordx4 v[142:143], off
	v_lshl_add_u64 v[142:143], s[4:5], 0, v[140:141]
	s_add_i32 m0, s23, 0xe000
	s_nop 0
	global_load_lds_dwordx4 v[142:143], off
	s_waitcnt vmcnt(8)
	s_waitcnt lgkmcnt(0)
	s_setprio 1
	s_barrier
	s_waitcnt lgkmcnt(0)
	v_mfma_f32_16x16x32_bf16 v[126:129], v[146:149], v[178:181], v[126:129]
	v_mfma_f32_16x16x32_bf16 v[122:125], v[154:157], v[178:181], v[122:125]
	v_mfma_f32_16x16x32_bf16 v[110:113], v[146:149], v[186:189], v[110:113]
	v_mfma_f32_16x16x32_bf16 v[106:109], v[154:157], v[186:189], v[106:109]
	v_mfma_f32_16x16x32_bf16 v[94:97], v[146:149], v[194:197], v[94:97]
	v_mfma_f32_16x16x32_bf16 v[90:93], v[154:157], v[194:197], v[90:93]
	v_mfma_f32_16x16x32_bf16 v[78:81], v[146:149], v[202:205], v[78:81]
	v_mfma_f32_16x16x32_bf16 v[74:77], v[154:157], v[202:205], v[74:77]
	v_mfma_f32_16x16x32_bf16 v[126:129], v[150:153], v[182:185], v[126:129]
	v_mfma_f32_16x16x32_bf16 v[122:125], v[158:161], v[182:185], v[122:125]
	v_mfma_f32_16x16x32_bf16 v[110:113], v[150:153], v[190:193], v[110:113]
	v_mfma_f32_16x16x32_bf16 v[106:109], v[158:161], v[190:193], v[106:109]
	v_mfma_f32_16x16x32_bf16 v[94:97], v[150:153], v[198:201], v[94:97]
	v_mfma_f32_16x16x32_bf16 v[90:93], v[158:161], v[198:201], v[90:93]
	v_mfma_f32_16x16x32_bf16 v[78:81], v[150:153], v[222:225], v[78:81]
	v_mfma_f32_16x16x32_bf16 v[74:77], v[158:161], v[222:225], v[74:77]
	s_setprio 0
	s_setprio 1
	v_mfma_f32_16x16x32_bf16 v[118:121], v[162:165], v[178:181], v[118:121]
	v_mfma_f32_16x16x32_bf16 v[114:117], v[170:173], v[178:181], v[114:117]
	v_mfma_f32_16x16x32_bf16 v[102:105], v[162:165], v[186:189], v[102:105]
	v_mfma_f32_16x16x32_bf16 v[98:101], v[170:173], v[186:189], v[98:101]
	v_mfma_f32_16x16x32_bf16 v[86:89], v[162:165], v[194:197], v[86:89]
	v_mfma_f32_16x16x32_bf16 v[82:85], v[170:173], v[194:197], v[82:85]
	v_mfma_f32_16x16x32_bf16 v[70:73], v[162:165], v[202:205], v[70:73]
	v_mfma_f32_16x16x32_bf16 v[66:69], v[170:173], v[202:205], v[66:69]
	v_mfma_f32_16x16x32_bf16 v[118:121], v[166:169], v[182:185], v[118:121]
	v_mfma_f32_16x16x32_bf16 v[114:117], v[174:177], v[182:185], v[114:117]
	v_mfma_f32_16x16x32_bf16 v[102:105], v[166:169], v[190:193], v[102:105]
	v_mfma_f32_16x16x32_bf16 v[98:101], v[174:177], v[190:193], v[98:101]
	v_mfma_f32_16x16x32_bf16 v[86:89], v[166:169], v[198:201], v[86:89]
	v_mfma_f32_16x16x32_bf16 v[82:85], v[174:177], v[198:201], v[82:85]
	v_mfma_f32_16x16x32_bf16 v[70:73], v[166:169], v[222:225], v[70:73]
	v_mfma_f32_16x16x32_bf16 v[66:69], v[174:177], v[222:225], v[66:69]
	s_barrier
	s_setprio 0
	s_add_i32 s4, s49, s30
	v_lshl_add_u64 v[142:143], s[26:27], 0, v[130:131]
	s_mov_b32 m0, s4
	ds_read_b128 v[178:181], v144 offset:16384
	ds_read_b128 v[182:185], v144 offset:17408
	ds_read_b128 v[186:189], v144 offset:18432
	ds_read_b128 v[190:193], v144 offset:19456
	ds_read_b128 v[194:197], v144 offset:20480
	ds_read_b128 v[198:201], v144 offset:21504
	ds_read_b128 v[202:205], v144 offset:22528
	ds_read_b128 v[222:225], v144 offset:23552
	global_load_lds_dwordx4 v[142:143], off
	s_add_i32 m0, s4, 0x2000
	s_add_u32 s4, s26, 0x40000
	v_lshl_add_u64 v[206:207], s[26:27], 0, v[132:133]
	s_addc_u32 s5, s27, 0
	s_add_i32 s49, s50, s30
	global_load_lds_dwordx4 v[206:207], off
	v_lshl_add_u64 v[218:219], s[4:5], 0, v[130:131]
	s_mov_b32 m0, s49
	v_lshl_add_u64 v[226:227], s[28:29], 0, v[132:133]
	global_load_lds_dwordx4 v[218:219], off
	v_lshl_add_u64 v[218:219], s[4:5], 0, v[132:133]
	s_add_i32 m0, s49, 0x2000
	s_nop 0
	global_load_lds_dwordx4 v[218:219], off
	v_lshl_add_u64 v[218:219], s[28:29], 0, v[130:131]
	s_mov_b32 m0, s23
	s_nop 0
	global_load_lds_dwordx4 v[218:219], off
	s_mov_b32 m0, s31
	s_nop 0
	global_load_lds_dwordx4 v[226:227], off
	s_waitcnt vmcnt(8)
	s_waitcnt lgkmcnt(0)
	s_setprio 1
	s_barrier
	s_waitcnt lgkmcnt(0)
	v_mfma_f32_16x16x32_bf16 v[62:65], v[146:149], v[178:181], v[62:65]
	v_mfma_f32_16x16x32_bf16 v[58:61], v[154:157], v[178:181], v[58:61]
	v_mfma_f32_16x16x32_bf16 v[46:49], v[146:149], v[186:189], v[46:49]
	v_mfma_f32_16x16x32_bf16 v[42:45], v[154:157], v[186:189], v[42:45]
	v_mfma_f32_16x16x32_bf16 v[30:33], v[146:149], v[194:197], v[30:33]
	v_mfma_f32_16x16x32_bf16 v[26:29], v[154:157], v[194:197], v[26:29]
	v_mfma_f32_16x16x32_bf16 v[14:17], v[146:149], v[202:205], v[14:17]
	v_mfma_f32_16x16x32_bf16 v[10:13], v[154:157], v[202:205], v[10:13]
	v_mfma_f32_16x16x32_bf16 v[62:65], v[150:153], v[182:185], v[62:65]
	v_mfma_f32_16x16x32_bf16 v[58:61], v[158:161], v[182:185], v[58:61]
	v_mfma_f32_16x16x32_bf16 v[46:49], v[150:153], v[190:193], v[46:49]
	v_mfma_f32_16x16x32_bf16 v[42:45], v[158:161], v[190:193], v[42:45]
	v_mfma_f32_16x16x32_bf16 v[30:33], v[150:153], v[198:201], v[30:33]
	v_mfma_f32_16x16x32_bf16 v[26:29], v[158:161], v[198:201], v[26:29]
	v_mfma_f32_16x16x32_bf16 v[14:17], v[150:153], v[222:225], v[14:17]
	v_mfma_f32_16x16x32_bf16 v[10:13], v[158:161], v[222:225], v[10:13]
	s_setprio 0
	s_setprio 1
	v_mfma_f32_16x16x32_bf16 v[54:57], v[162:165], v[178:181], v[54:57]
	v_mfma_f32_16x16x32_bf16 v[50:53], v[170:173], v[178:181], v[50:53]
	v_mfma_f32_16x16x32_bf16 v[38:41], v[162:165], v[186:189], v[38:41]
	v_mfma_f32_16x16x32_bf16 v[34:37], v[170:173], v[186:189], v[34:37]
	v_mfma_f32_16x16x32_bf16 v[22:25], v[162:165], v[194:197], v[22:25]
	v_mfma_f32_16x16x32_bf16 v[18:21], v[170:173], v[194:197], v[18:21]
	v_mfma_f32_16x16x32_bf16 v[6:9], v[162:165], v[202:205], v[6:9]
	v_mfma_f32_16x16x32_bf16 v[2:5], v[170:173], v[202:205], v[2:5]
	v_mfma_f32_16x16x32_bf16 v[54:57], v[166:169], v[182:185], v[54:57]
	v_mfma_f32_16x16x32_bf16 v[50:53], v[174:177], v[182:185], v[50:53]
	v_mfma_f32_16x16x32_bf16 v[38:41], v[166:169], v[190:193], v[38:41]
	v_mfma_f32_16x16x32_bf16 v[34:37], v[174:177], v[190:193], v[34:37]
	v_mfma_f32_16x16x32_bf16 v[22:25], v[166:169], v[198:201], v[22:25]
	v_mfma_f32_16x16x32_bf16 v[18:21], v[174:177], v[198:201], v[18:21]
	v_mfma_f32_16x16x32_bf16 v[6:9], v[166:169], v[222:225], v[6:9]
	v_mfma_f32_16x16x32_bf16 v[2:5], v[174:177], v[222:225], v[2:5]
	s_barrier
	s_setprio 0
	s_add_i32 s49, 0, 0x18000
	v_add_u32_e32 v0, s49, v135
	s_add_i32 s50, 0, 0x1c000
	ds_read_b128 v[146:149], v0
	ds_read_b128 v[150:153], v0 offset:1024
	ds_read_b128 v[154:157], v0 offset:2048
	ds_read_b128 v[158:161], v0 offset:3072
	v_add_u32_e32 v0, s50, v135
	ds_read_b128 v[162:165], v0
	ds_read_b128 v[166:169], v0 offset:1024
	ds_read_b128 v[170:173], v0 offset:2048
	ds_read_b128 v[174:177], v0 offset:3072
	s_add_u32 s4, s28, 0x40000
	s_addc_u32 s5, s29, 0
	s_mov_b32 m0, s33
	v_lshl_add_u64 v[228:229], s[4:5], 0, v[130:131]
	ds_read_b128 v[178:181], v144 offset:32768
	ds_read_b128 v[182:185], v144 offset:33792
	ds_read_b128 v[186:189], v144 offset:34816
	ds_read_b128 v[190:193], v144 offset:35840
	ds_read_b128 v[194:197], v144 offset:36864
	ds_read_b128 v[198:201], v144 offset:37888
	ds_read_b128 v[202:205], v144 offset:38912
	ds_read_b128 v[222:225], v144 offset:39936
	global_load_lds_dwordx4 v[228:229], off
	v_lshl_add_u64 v[228:229], s[4:5], 0, v[132:133]
	s_mov_b32 m0, s34
	s_nop 0
	global_load_lds_dwordx4 v[228:229], off
	s_waitcnt vmcnt(8)
	s_waitcnt lgkmcnt(0)
	s_setprio 1
	s_barrier
	s_waitcnt lgkmcnt(0)
	v_mfma_f32_16x16x32_bf16 v[126:129], v[146:149], v[178:181], v[126:129]
	v_mfma_f32_16x16x32_bf16 v[122:125], v[154:157], v[178:181], v[122:125]
	v_mfma_f32_16x16x32_bf16 v[110:113], v[146:149], v[186:189], v[110:113]
	v_mfma_f32_16x16x32_bf16 v[106:109], v[154:157], v[186:189], v[106:109]
	v_mfma_f32_16x16x32_bf16 v[94:97], v[146:149], v[194:197], v[94:97]
	v_mfma_f32_16x16x32_bf16 v[90:93], v[154:157], v[194:197], v[90:93]
	v_mfma_f32_16x16x32_bf16 v[78:81], v[146:149], v[202:205], v[78:81]
	v_mfma_f32_16x16x32_bf16 v[74:77], v[154:157], v[202:205], v[74:77]
	v_mfma_f32_16x16x32_bf16 v[126:129], v[150:153], v[182:185], v[126:129]
	v_mfma_f32_16x16x32_bf16 v[122:125], v[158:161], v[182:185], v[122:125]
	v_mfma_f32_16x16x32_bf16 v[110:113], v[150:153], v[190:193], v[110:113]
	v_mfma_f32_16x16x32_bf16 v[106:109], v[158:161], v[190:193], v[106:109]
	v_mfma_f32_16x16x32_bf16 v[94:97], v[150:153], v[198:201], v[94:97]
	v_mfma_f32_16x16x32_bf16 v[90:93], v[158:161], v[198:201], v[90:93]
	v_mfma_f32_16x16x32_bf16 v[78:81], v[150:153], v[222:225], v[78:81]
	v_mfma_f32_16x16x32_bf16 v[74:77], v[158:161], v[222:225], v[74:77]
	s_setprio 0
	s_setprio 1
	v_mfma_f32_16x16x32_bf16 v[118:121], v[162:165], v[178:181], v[118:121]
	v_mfma_f32_16x16x32_bf16 v[114:117], v[170:173], v[178:181], v[114:117]
	v_mfma_f32_16x16x32_bf16 v[102:105], v[162:165], v[186:189], v[102:105]
	v_mfma_f32_16x16x32_bf16 v[98:101], v[170:173], v[186:189], v[98:101]
	v_mfma_f32_16x16x32_bf16 v[86:89], v[162:165], v[194:197], v[86:89]
	v_mfma_f32_16x16x32_bf16 v[82:85], v[170:173], v[194:197], v[82:85]
	v_mfma_f32_16x16x32_bf16 v[70:73], v[162:165], v[202:205], v[70:73]
	v_mfma_f32_16x16x32_bf16 v[66:69], v[170:173], v[202:205], v[66:69]
	v_mfma_f32_16x16x32_bf16 v[118:121], v[166:169], v[182:185], v[118:121]
	v_mfma_f32_16x16x32_bf16 v[114:117], v[174:177], v[182:185], v[114:117]
	v_mfma_f32_16x16x32_bf16 v[102:105], v[166:169], v[190:193], v[102:105]
	v_mfma_f32_16x16x32_bf16 v[98:101], v[174:177], v[190:193], v[98:101]
	v_mfma_f32_16x16x32_bf16 v[86:89], v[166:169], v[198:201], v[86:89]
	v_mfma_f32_16x16x32_bf16 v[82:85], v[174:177], v[198:201], v[82:85]
	v_mfma_f32_16x16x32_bf16 v[70:73], v[166:169], v[222:225], v[70:73]
	v_mfma_f32_16x16x32_bf16 v[66:69], v[174:177], v[222:225], v[66:69]
	s_barrier
	s_setprio 0
	s_add_i32 s4, s49, s30
	v_lshl_add_u64 v[142:143], v[142:143], 0, s[44:45]
	s_mov_b32 m0, s4
	ds_read_b128 v[178:181], v144 offset:49152
	ds_read_b128 v[182:185], v144 offset:50176
	ds_read_b128 v[186:189], v144 offset:51200
	ds_read_b128 v[190:193], v144 offset:52224
	ds_read_b128 v[194:197], v144 offset:53248
	ds_read_b128 v[198:201], v144 offset:54272
	ds_read_b128 v[202:205], v144 offset:55296
	ds_read_b128 v[222:225], v144 offset:56320
	global_load_lds_dwordx4 v[142:143], off
	s_add_i32 m0, s4, 0x2000
	s_add_u32 s4, s26, 0x40080
	v_lshl_add_u64 v[142:143], v[206:207], 0, s[44:45]
	s_addc_u32 s5, s27, 0
	s_add_i32 s26, s50, s30
	global_load_lds_dwordx4 v[142:143], off
	v_lshl_add_u64 v[142:143], s[4:5], 0, v[130:131]
	s_mov_b32 m0, s26
	s_nop 0
	global_load_lds_dwordx4 v[142:143], off
	v_lshl_add_u64 v[142:143], s[4:5], 0, v[132:133]
	s_add_i32 m0, s26, 0x2000
	s_nop 0
	global_load_lds_dwordx4 v[142:143], off
	v_lshl_add_u64 v[142:143], v[218:219], 0, s[44:45]
	s_mov_b32 m0, s37
	s_nop 0
	global_load_lds_dwordx4 v[142:143], off
	v_lshl_add_u64 v[142:143], v[226:227], 0, s[44:45]
	s_mov_b32 m0, s38
	s_nop 0
	global_load_lds_dwordx4 v[142:143], off
	s_waitcnt vmcnt(8)
	s_waitcnt lgkmcnt(0)
	s_setprio 1
	s_barrier
	s_waitcnt lgkmcnt(0)
	v_mfma_f32_16x16x32_bf16 v[62:65], v[146:149], v[178:181], v[62:65]
	v_mfma_f32_16x16x32_bf16 v[58:61], v[154:157], v[178:181], v[58:61]
	v_mfma_f32_16x16x32_bf16 v[46:49], v[146:149], v[186:189], v[46:49]
	v_mfma_f32_16x16x32_bf16 v[42:45], v[154:157], v[186:189], v[42:45]
	v_mfma_f32_16x16x32_bf16 v[30:33], v[146:149], v[194:197], v[30:33]
	v_mfma_f32_16x16x32_bf16 v[26:29], v[154:157], v[194:197], v[26:29]
	v_mfma_f32_16x16x32_bf16 v[14:17], v[146:149], v[202:205], v[14:17]
	v_mfma_f32_16x16x32_bf16 v[10:13], v[154:157], v[202:205], v[10:13]
	v_mfma_f32_16x16x32_bf16 v[62:65], v[150:153], v[182:185], v[62:65]
	v_mfma_f32_16x16x32_bf16 v[58:61], v[158:161], v[182:185], v[58:61]
	v_mfma_f32_16x16x32_bf16 v[46:49], v[150:153], v[190:193], v[46:49]
	v_mfma_f32_16x16x32_bf16 v[42:45], v[158:161], v[190:193], v[42:45]
	v_mfma_f32_16x16x32_bf16 v[30:33], v[150:153], v[198:201], v[30:33]
	v_mfma_f32_16x16x32_bf16 v[26:29], v[158:161], v[198:201], v[26:29]
	v_mfma_f32_16x16x32_bf16 v[14:17], v[150:153], v[222:225], v[14:17]
	v_mfma_f32_16x16x32_bf16 v[10:13], v[158:161], v[222:225], v[10:13]
	s_setprio 0
	s_setprio 1
	v_mfma_f32_16x16x32_bf16 v[54:57], v[162:165], v[178:181], v[54:57]
	v_mfma_f32_16x16x32_bf16 v[50:53], v[170:173], v[178:181], v[50:53]
	v_mfma_f32_16x16x32_bf16 v[38:41], v[162:165], v[186:189], v[38:41]
	v_mfma_f32_16x16x32_bf16 v[34:37], v[170:173], v[186:189], v[34:37]
	v_mfma_f32_16x16x32_bf16 v[22:25], v[162:165], v[194:197], v[22:25]
	v_mfma_f32_16x16x32_bf16 v[18:21], v[170:173], v[194:197], v[18:21]
	v_mfma_f32_16x16x32_bf16 v[6:9], v[162:165], v[202:205], v[6:9]
	v_mfma_f32_16x16x32_bf16 v[2:5], v[170:173], v[202:205], v[2:5]
	v_mfma_f32_16x16x32_bf16 v[54:57], v[166:169], v[182:185], v[54:57]
	v_mfma_f32_16x16x32_bf16 v[50:53], v[174:177], v[182:185], v[50:53]
	v_mfma_f32_16x16x32_bf16 v[38:41], v[166:169], v[190:193], v[38:41]
	v_mfma_f32_16x16x32_bf16 v[34:37], v[174:177], v[190:193], v[34:37]
	v_mfma_f32_16x16x32_bf16 v[22:25], v[166:169], v[198:201], v[22:25]
	v_mfma_f32_16x16x32_bf16 v[18:21], v[174:177], v[198:201], v[18:21]
	v_mfma_f32_16x16x32_bf16 v[6:9], v[166:169], v[222:225], v[6:9]
	v_mfma_f32_16x16x32_bf16 v[2:5], v[174:177], v[222:225], v[2:5]
	s_barrier
	s_setprio 0
	s_add_i32 s48, s48, 2
	s_add_u32 s46, s46, 0x100
	s_addc_u32 s47, s47, 0
	s_cmp_gt_u32 s48, 13
	s_mov_b64 s[4:5], s[2:3]
	s_cbranch_scc0 .LBB0_650
	s_and_b64 vcc, exec, s[12:13]
	s_cbranch_vccz .LBB0_653
	s_barrier

.LBB0_783:
	s_add_u32 s2, s4, 0xfffc0080
	s_addc_u32 s3, s5, -1
	s_add_i32 s48, 0, 0x10000
	s_cmp_eq_u32 s47, 12
	s_cselect_b32 s27, s17, s3
	s_cselect_b32 s26, s25, s2
	s_cselect_b32 s3, s15, s46
	s_cselect_b32 s2, s41, s42
	s_add_i32 s50, 0, 0x14000
	v_add_u32_e32 v154, s48, v140
	v_add_u32_e32 v170, s50, v140
	ds_read_b128 v[142:145], v154
	ds_read_b128 v[146:149], v154 offset:1024
	ds_read_b128 v[150:153], v154 offset:2048
	ds_read_b128 v[154:157], v154 offset:3072
	ds_read_b128 v[158:161], v170
	ds_read_b128 v[162:165], v170 offset:1024
	ds_read_b128 v[166:169], v170 offset:2048
	ds_read_b128 v[170:173], v170 offset:3072
	v_lshl_add_u64 v[206:207], s[4:5], 0, v[136:137]
	s_add_i32 m0, s23, 0xc000
	ds_read_b128 v[174:177], v141
	ds_read_b128 v[178:181], v141 offset:1024
	ds_read_b128 v[182:185], v141 offset:2048
	ds_read_b128 v[186:189], v141 offset:3072
	ds_read_b128 v[190:193], v141 offset:4096
	ds_read_b128 v[194:197], v141 offset:5120
	ds_read_b128 v[198:201], v141 offset:6144
	ds_read_b128 v[202:205], v141 offset:7168
	global_load_lds_dwordx4 v[206:207], off
	v_lshl_add_u64 v[206:207], s[4:5], 0, v[138:139]
	s_add_i32 m0, s23, 0xe000
	s_nop 0
	global_load_lds_dwordx4 v[206:207], off
	s_waitcnt vmcnt(8)
	s_waitcnt lgkmcnt(0)
	s_setprio 1
	s_barrier
	s_waitcnt lgkmcnt(0)
	v_mfma_f32_16x16x32_bf16 v[122:125], v[142:145], v[174:177], v[122:125]
	v_mfma_f32_16x16x32_bf16 v[114:117], v[150:153], v[174:177], v[114:117]
	v_mfma_f32_16x16x32_bf16 v[106:109], v[142:145], v[182:185], v[106:109]
	v_mfma_f32_16x16x32_bf16 v[98:101], v[150:153], v[182:185], v[98:101]
	v_mfma_f32_16x16x32_bf16 v[90:93], v[142:145], v[190:193], v[90:93]
	v_mfma_f32_16x16x32_bf16 v[82:85], v[150:153], v[190:193], v[82:85]
	v_mfma_f32_16x16x32_bf16 v[74:77], v[142:145], v[198:201], v[74:77]
	v_mfma_f32_16x16x32_bf16 v[66:69], v[150:153], v[198:201], v[66:69]
	v_mfma_f32_16x16x32_bf16 v[122:125], v[146:149], v[178:181], v[122:125]
	v_mfma_f32_16x16x32_bf16 v[114:117], v[154:157], v[178:181], v[114:117]
	v_mfma_f32_16x16x32_bf16 v[106:109], v[146:149], v[186:189], v[106:109]
	v_mfma_f32_16x16x32_bf16 v[98:101], v[154:157], v[186:189], v[98:101]
	v_mfma_f32_16x16x32_bf16 v[90:93], v[146:149], v[194:197], v[90:93]
	v_mfma_f32_16x16x32_bf16 v[82:85], v[154:157], v[194:197], v[82:85]
	v_mfma_f32_16x16x32_bf16 v[74:77], v[146:149], v[202:205], v[74:77]
	v_mfma_f32_16x16x32_bf16 v[66:69], v[154:157], v[202:205], v[66:69]
	s_setprio 0
	s_setprio 1
	v_mfma_f32_16x16x32_bf16 v[126:129], v[158:161], v[174:177], v[126:129]
	v_mfma_f32_16x16x32_bf16 v[118:121], v[166:169], v[174:177], v[118:121]
	v_mfma_f32_16x16x32_bf16 v[110:113], v[158:161], v[182:185], v[110:113]
	v_mfma_f32_16x16x32_bf16 v[102:105], v[166:169], v[182:185], v[102:105]
	v_mfma_f32_16x16x32_bf16 v[94:97], v[158:161], v[190:193], v[94:97]
	v_mfma_f32_16x16x32_bf16 v[86:89], v[166:169], v[190:193], v[86:89]
	v_mfma_f32_16x16x32_bf16 v[78:81], v[158:161], v[198:201], v[78:81]
	v_mfma_f32_16x16x32_bf16 v[70:73], v[166:169], v[198:201], v[70:73]
	v_mfma_f32_16x16x32_bf16 v[126:129], v[162:165], v[178:181], v[126:129]
	v_mfma_f32_16x16x32_bf16 v[118:121], v[170:173], v[178:181], v[118:121]
	v_mfma_f32_16x16x32_bf16 v[110:113], v[162:165], v[186:189], v[110:113]
	v_mfma_f32_16x16x32_bf16 v[102:105], v[170:173], v[186:189], v[102:105]
	v_mfma_f32_16x16x32_bf16 v[94:97], v[162:165], v[194:197], v[94:97]
	v_mfma_f32_16x16x32_bf16 v[86:89], v[170:173], v[194:197], v[86:89]
	v_mfma_f32_16x16x32_bf16 v[78:81], v[162:165], v[202:205], v[78:81]
	v_mfma_f32_16x16x32_bf16 v[70:73], v[170:173], v[202:205], v[70:73]
	s_barrier
	s_setprio 0
	s_add_i32 s48, s48, s28
	v_lshl_add_u64 v[206:207], s[2:3], 0, v[132:133]
	s_mov_b32 m0, s48
	ds_read_b128 v[174:177], v141 offset:16384
	ds_read_b128 v[178:181], v141 offset:17408
	ds_read_b128 v[182:185], v141 offset:18432
	ds_read_b128 v[186:189], v141 offset:19456
	ds_read_b128 v[190:193], v141 offset:20480
	ds_read_b128 v[194:197], v141 offset:21504
	ds_read_b128 v[198:201], v141 offset:22528
	ds_read_b128 v[202:205], v141 offset:23552
	global_load_lds_dwordx4 v[206:207], off
	s_add_i32 m0, s48, 0x2000
	s_add_u32 s48, s2, 0x40000
	v_lshl_add_u64 v[218:219], s[2:3], 0, v[130:131]
	s_addc_u32 s49, s3, 0
	s_add_i32 s50, s50, s28
	global_load_lds_dwordx4 v[218:219], off
	v_lshl_add_u64 v[222:223], s[48:49], 0, v[132:133]
	s_mov_b32 m0, s50
	v_lshl_add_u64 v[224:225], s[26:27], 0, v[130:131]
	global_load_lds_dwordx4 v[222:223], off
	v_lshl_add_u64 v[222:223], s[48:49], 0, v[130:131]
	s_add_i32 m0, s50, 0x2000
	s_nop 0
	global_load_lds_dwordx4 v[222:223], off
	v_lshl_add_u64 v[222:223], s[26:27], 0, v[132:133]
	s_mov_b32 m0, s23
	s_nop 0
	global_load_lds_dwordx4 v[222:223], off
	s_mov_b32 m0, s31
	s_nop 0
	global_load_lds_dwordx4 v[224:225], off
	s_waitcnt vmcnt(8)
	s_waitcnt lgkmcnt(0)
	s_setprio 1
	s_barrier
	s_waitcnt lgkmcnt(0)
	v_mfma_f32_16x16x32_bf16 v[58:61], v[142:145], v[174:177], v[58:61]
	v_mfma_f32_16x16x32_bf16 v[50:53], v[150:153], v[174:177], v[50:53]
	v_mfma_f32_16x16x32_bf16 v[42:45], v[142:145], v[182:185], v[42:45]
	v_mfma_f32_16x16x32_bf16 v[34:37], v[150:153], v[182:185], v[34:37]
	v_mfma_f32_16x16x32_bf16 v[26:29], v[142:145], v[190:193], v[26:29]
	v_mfma_f32_16x16x32_bf16 v[18:21], v[150:153], v[190:193], v[18:21]
	v_mfma_f32_16x16x32_bf16 v[10:13], v[142:145], v[198:201], v[10:13]
	v_mfma_f32_16x16x32_bf16 v[2:5], v[150:153], v[198:201], v[2:5]
	v_mfma_f32_16x16x32_bf16 v[58:61], v[146:149], v[178:181], v[58:61]
	v_mfma_f32_16x16x32_bf16 v[50:53], v[154:157], v[178:181], v[50:53]
	v_mfma_f32_16x16x32_bf16 v[42:45], v[146:149], v[186:189], v[42:45]
	v_mfma_f32_16x16x32_bf16 v[34:37], v[154:157], v[186:189], v[34:37]
	v_mfma_f32_16x16x32_bf16 v[26:29], v[146:149], v[194:197], v[26:29]
	v_mfma_f32_16x16x32_bf16 v[18:21], v[154:157], v[194:197], v[18:21]
	v_mfma_f32_16x16x32_bf16 v[10:13], v[146:149], v[202:205], v[10:13]
	v_mfma_f32_16x16x32_bf16 v[2:5], v[154:157], v[202:205], v[2:5]
	s_setprio 0
	s_setprio 1
	v_mfma_f32_16x16x32_bf16 v[62:65], v[158:161], v[174:177], v[62:65]
	v_mfma_f32_16x16x32_bf16 v[54:57], v[166:169], v[174:177], v[54:57]
	v_mfma_f32_16x16x32_bf16 v[46:49], v[158:161], v[182:185], v[46:49]
	v_mfma_f32_16x16x32_bf16 v[38:41], v[166:169], v[182:185], v[38:41]
	v_mfma_f32_16x16x32_bf16 v[30:33], v[158:161], v[190:193], v[30:33]
	v_mfma_f32_16x16x32_bf16 v[22:25], v[166:169], v[190:193], v[22:25]
	v_mfma_f32_16x16x32_bf16 v[14:17], v[158:161], v[198:201], v[14:17]
	v_mfma_f32_16x16x32_bf16 v[6:9], v[166:169], v[198:201], v[6:9]
	v_mfma_f32_16x16x32_bf16 v[62:65], v[162:165], v[178:181], v[62:65]
	v_mfma_f32_16x16x32_bf16 v[54:57], v[170:173], v[178:181], v[54:57]
	v_mfma_f32_16x16x32_bf16 v[46:49], v[162:165], v[186:189], v[46:49]
	v_mfma_f32_16x16x32_bf16 v[38:41], v[170:173], v[186:189], v[38:41]
	v_mfma_f32_16x16x32_bf16 v[30:33], v[162:165], v[194:197], v[30:33]
	v_mfma_f32_16x16x32_bf16 v[22:25], v[170:173], v[194:197], v[22:25]
	v_mfma_f32_16x16x32_bf16 v[14:17], v[162:165], v[202:205], v[14:17]
	v_mfma_f32_16x16x32_bf16 v[6:9], v[170:173], v[202:205], v[6:9]
	s_barrier
	s_setprio 0
	s_add_i32 s48, 0, 0x18000
	s_add_i32 s49, 0, 0x1c000
	v_add_u32_e32 v154, s48, v140
	v_add_u32_e32 v170, s49, v140
	ds_read_b128 v[142:145], v154
	ds_read_b128 v[146:149], v154 offset:1024
	ds_read_b128 v[150:153], v154 offset:2048
	ds_read_b128 v[154:157], v154 offset:3072
	ds_read_b128 v[158:161], v170
	ds_read_b128 v[162:165], v170 offset:1024
	ds_read_b128 v[166:169], v170 offset:2048
	ds_read_b128 v[170:173], v170 offset:3072
	s_add_u32 s26, s26, 0x40000
	s_addc_u32 s27, s27, 0
	s_mov_b32 m0, s33
	v_lshl_add_u64 v[226:227], s[26:27], 0, v[132:133]
	ds_read_b128 v[174:177], v141 offset:32768
	ds_read_b128 v[178:181], v141 offset:33792
	ds_read_b128 v[182:185], v141 offset:34816
	ds_read_b128 v[186:189], v141 offset:35840
	ds_read_b128 v[190:193], v141 offset:36864
	ds_read_b128 v[194:197], v141 offset:37888
	ds_read_b128 v[198:201], v141 offset:38912
	ds_read_b128 v[202:205], v141 offset:39936
	global_load_lds_dwordx4 v[226:227], off
	v_lshl_add_u64 v[226:227], s[26:27], 0, v[130:131]
	s_mov_b32 m0, s34
	s_nop 0
	global_load_lds_dwordx4 v[226:227], off
	s_waitcnt vmcnt(8)
	s_waitcnt lgkmcnt(0)
	s_setprio 1
	s_barrier
	s_waitcnt lgkmcnt(0)
	v_mfma_f32_16x16x32_bf16 v[122:125], v[142:145], v[174:177], v[122:125]
	v_mfma_f32_16x16x32_bf16 v[114:117], v[150:153], v[174:177], v[114:117]
	v_mfma_f32_16x16x32_bf16 v[106:109], v[142:145], v[182:185], v[106:109]
	v_mfma_f32_16x16x32_bf16 v[98:101], v[150:153], v[182:185], v[98:101]
	v_mfma_f32_16x16x32_bf16 v[90:93], v[142:145], v[190:193], v[90:93]
	v_mfma_f32_16x16x32_bf16 v[82:85], v[150:153], v[190:193], v[82:85]
	v_mfma_f32_16x16x32_bf16 v[74:77], v[142:145], v[198:201], v[74:77]
	v_mfma_f32_16x16x32_bf16 v[66:69], v[150:153], v[198:201], v[66:69]
	v_mfma_f32_16x16x32_bf16 v[122:125], v[146:149], v[178:181], v[122:125]
	v_mfma_f32_16x16x32_bf16 v[114:117], v[154:157], v[178:181], v[114:117]
	v_mfma_f32_16x16x32_bf16 v[106:109], v[146:149], v[186:189], v[106:109]
	v_mfma_f32_16x16x32_bf16 v[98:101], v[154:157], v[186:189], v[98:101]
	v_mfma_f32_16x16x32_bf16 v[90:93], v[146:149], v[194:197], v[90:93]
	v_mfma_f32_16x16x32_bf16 v[82:85], v[154:157], v[194:197], v[82:85]
	v_mfma_f32_16x16x32_bf16 v[74:77], v[146:149], v[202:205], v[74:77]
	v_mfma_f32_16x16x32_bf16 v[66:69], v[154:157], v[202:205], v[66:69]
	s_setprio 0
	s_setprio 1
	v_mfma_f32_16x16x32_bf16 v[126:129], v[158:161], v[174:177], v[126:129]
	v_mfma_f32_16x16x32_bf16 v[118:121], v[166:169], v[174:177], v[118:121]
	v_mfma_f32_16x16x32_bf16 v[110:113], v[158:161], v[182:185], v[110:113]
	v_mfma_f32_16x16x32_bf16 v[102:105], v[166:169], v[182:185], v[102:105]
	v_mfma_f32_16x16x32_bf16 v[94:97], v[158:161], v[190:193], v[94:97]
	v_mfma_f32_16x16x32_bf16 v[86:89], v[166:169], v[190:193], v[86:89]
	v_mfma_f32_16x16x32_bf16 v[78:81], v[158:161], v[198:201], v[78:81]
	v_mfma_f32_16x16x32_bf16 v[70:73], v[166:169], v[198:201], v[70:73]
	v_mfma_f32_16x16x32_bf16 v[126:129], v[162:165], v[178:181], v[126:129]
	v_mfma_f32_16x16x32_bf16 v[118:121], v[170:173], v[178:181], v[118:121]
	v_mfma_f32_16x16x32_bf16 v[110:113], v[162:165], v[186:189], v[110:113]
	v_mfma_f32_16x16x32_bf16 v[102:105], v[170:173], v[186:189], v[102:105]
	v_mfma_f32_16x16x32_bf16 v[94:97], v[162:165], v[194:197], v[94:97]
	v_mfma_f32_16x16x32_bf16 v[86:89], v[170:173], v[194:197], v[86:89]
	v_mfma_f32_16x16x32_bf16 v[78:81], v[162:165], v[202:205], v[78:81]
	v_mfma_f32_16x16x32_bf16 v[70:73], v[170:173], v[202:205], v[70:73]
	s_barrier
	s_setprio 0
	s_add_i32 s26, s48, s28
	v_lshl_add_u64 v[206:207], v[206:207], 0, s[44:45]
	s_mov_b32 m0, s26
	ds_read_b128 v[174:177], v141 offset:49152
	ds_read_b128 v[178:181], v141 offset:50176
	ds_read_b128 v[182:185], v141 offset:51200
	ds_read_b128 v[186:189], v141 offset:52224
	ds_read_b128 v[190:193], v141 offset:53248
	ds_read_b128 v[194:197], v141 offset:54272
	ds_read_b128 v[198:201], v141 offset:55296
	ds_read_b128 v[202:205], v141 offset:56320
	global_load_lds_dwordx4 v[206:207], off
	s_add_i32 m0, s26, 0x2000
	s_add_u32 s2, s2, 0x40080
	v_lshl_add_u64 v[206:207], v[218:219], 0, s[44:45]
	s_addc_u32 s3, s3, 0
	s_add_i32 s26, s49, s28
	global_load_lds_dwordx4 v[206:207], off
	v_lshl_add_u64 v[206:207], s[2:3], 0, v[132:133]
	s_mov_b32 m0, s26
	s_nop 0
	global_load_lds_dwordx4 v[206:207], off
	v_lshl_add_u64 v[206:207], s[2:3], 0, v[130:131]
	s_add_i32 m0, s26, 0x2000
	s_nop 0
	global_load_lds_dwordx4 v[206:207], off
	v_lshl_add_u64 v[206:207], v[222:223], 0, s[44:45]
	s_mov_b32 m0, s35
	s_nop 0
	global_load_lds_dwordx4 v[206:207], off
	v_lshl_add_u64 v[206:207], v[224:225], 0, s[44:45]
	s_mov_b32 m0, s36
	s_nop 0
	global_load_lds_dwordx4 v[206:207], off
	s_waitcnt vmcnt(8)
	s_waitcnt lgkmcnt(0)
	s_setprio 1
	s_barrier
	s_waitcnt lgkmcnt(0)
	v_mfma_f32_16x16x32_bf16 v[58:61], v[142:145], v[174:177], v[58:61]
	v_mfma_f32_16x16x32_bf16 v[50:53], v[150:153], v[174:177], v[50:53]
	v_mfma_f32_16x16x32_bf16 v[42:45], v[142:145], v[182:185], v[42:45]
	v_mfma_f32_16x16x32_bf16 v[34:37], v[150:153], v[182:185], v[34:37]
	v_mfma_f32_16x16x32_bf16 v[26:29], v[142:145], v[190:193], v[26:29]
	v_mfma_f32_16x16x32_bf16 v[18:21], v[150:153], v[190:193], v[18:21]
	v_mfma_f32_16x16x32_bf16 v[10:13], v[142:145], v[198:201], v[10:13]
	v_mfma_f32_16x16x32_bf16 v[2:5], v[150:153], v[198:201], v[2:5]
	v_mfma_f32_16x16x32_bf16 v[58:61], v[146:149], v[178:181], v[58:61]
	v_mfma_f32_16x16x32_bf16 v[50:53], v[154:157], v[178:181], v[50:53]
	v_mfma_f32_16x16x32_bf16 v[42:45], v[146:149], v[186:189], v[42:45]
	v_mfma_f32_16x16x32_bf16 v[34:37], v[154:157], v[186:189], v[34:37]
	v_mfma_f32_16x16x32_bf16 v[26:29], v[146:149], v[194:197], v[26:29]
	v_mfma_f32_16x16x32_bf16 v[18:21], v[154:157], v[194:197], v[18:21]
	v_mfma_f32_16x16x32_bf16 v[10:13], v[146:149], v[202:205], v[10:13]
	v_mfma_f32_16x16x32_bf16 v[2:5], v[154:157], v[202:205], v[2:5]
	s_setprio 0
	s_setprio 1
	v_mfma_f32_16x16x32_bf16 v[62:65], v[158:161], v[174:177], v[62:65]
	v_mfma_f32_16x16x32_bf16 v[54:57], v[166:169], v[174:177], v[54:57]
	v_mfma_f32_16x16x32_bf16 v[46:49], v[158:161], v[182:185], v[46:49]
	v_mfma_f32_16x16x32_bf16 v[38:41], v[166:169], v[182:185], v[38:41]
	v_mfma_f32_16x16x32_bf16 v[30:33], v[158:161], v[190:193], v[30:33]
	v_mfma_f32_16x16x32_bf16 v[22:25], v[166:169], v[190:193], v[22:25]
	v_mfma_f32_16x16x32_bf16 v[14:17], v[158:161], v[198:201], v[14:17]
	v_mfma_f32_16x16x32_bf16 v[6:9], v[166:169], v[198:201], v[6:9]
	v_mfma_f32_16x16x32_bf16 v[62:65], v[162:165], v[178:181], v[62:65]
	v_mfma_f32_16x16x32_bf16 v[54:57], v[170:173], v[178:181], v[54:57]
	v_mfma_f32_16x16x32_bf16 v[46:49], v[162:165], v[186:189], v[46:49]
	v_mfma_f32_16x16x32_bf16 v[38:41], v[170:173], v[186:189], v[38:41]
	v_mfma_f32_16x16x32_bf16 v[30:33], v[162:165], v[194:197], v[30:33]
	v_mfma_f32_16x16x32_bf16 v[22:25], v[170:173], v[194:197], v[22:25]
	v_mfma_f32_16x16x32_bf16 v[14:17], v[162:165], v[202:205], v[14:17]
	v_mfma_f32_16x16x32_bf16 v[6:9], v[170:173], v[202:205], v[6:9]
	s_barrier
	s_setprio 0
	s_add_i32 s47, s47, 2
	s_add_u32 s4, s4, 0x100
	s_addc_u32 s5, s5, 0
	s_add_u32 s42, s42, 0x100
	s_addc_u32 s46, s46, 0
	s_cmp_gt_u32 s47, 13
	s_cbranch_scc0 .LBB0_783
	s_and_b64 vcc, exec, s[12:13]
	s_cbranch_vccz .LBB0_786
	s_barrier

.LBB0_849:
	s_add_u32 s2, s18, 0x100
	s_addc_u32 s3, s19, 0
	s_add_i32 s47, 0, 0x10000
	s_cmp_eq_u32 s46, 40
	s_cselect_b32 s23, s9, s3
	s_cselect_b32 s22, s8, s2
	v_add_u32_e32 v0, s47, v135
	s_cselect_b32 s21, s15, s42
	s_cselect_b32 s20, s14, s17
	s_add_i32 s48, 0, 0x14000
	ds_read_b128 v[146:149], v0
	ds_read_b128 v[150:153], v0 offset:1024
	ds_read_b128 v[154:157], v0 offset:2048
	ds_read_b128 v[158:161], v0 offset:3072
	v_add_u32_e32 v0, s48, v135
	ds_read_b128 v[162:165], v0
	ds_read_b128 v[166:169], v0 offset:1024
	ds_read_b128 v[170:173], v0 offset:2048
	ds_read_b128 v[174:177], v0 offset:3072
	v_lshl_add_u64 v[142:143], s[18:19], 0, v[138:139]
	s_add_i32 m0, s25, 0xc000
	ds_read_b128 v[178:181], v144
	ds_read_b128 v[182:185], v144 offset:1024
	ds_read_b128 v[186:189], v144 offset:2048
	ds_read_b128 v[190:193], v144 offset:3072
	ds_read_b128 v[194:197], v144 offset:4096
	ds_read_b128 v[198:201], v144 offset:5120
	ds_read_b128 v[202:205], v144 offset:6144
	ds_read_b128 v[222:225], v144 offset:7168
	global_load_lds_dwordx4 v[142:143], off
	v_lshl_add_u64 v[142:143], s[18:19], 0, v[140:141]
	s_add_i32 m0, s25, 0xe000
	s_nop 0
	global_load_lds_dwordx4 v[142:143], off
	s_waitcnt vmcnt(8)
	s_waitcnt lgkmcnt(0)
	s_setprio 1
	s_barrier
	s_waitcnt lgkmcnt(0)
	v_mfma_f32_16x16x32_bf16 v[126:129], v[146:149], v[178:181], v[126:129]
	v_mfma_f32_16x16x32_bf16 v[122:125], v[154:157], v[178:181], v[122:125]
	v_mfma_f32_16x16x32_bf16 v[110:113], v[146:149], v[186:189], v[110:113]
	v_mfma_f32_16x16x32_bf16 v[106:109], v[154:157], v[186:189], v[106:109]
	v_mfma_f32_16x16x32_bf16 v[94:97], v[146:149], v[194:197], v[94:97]
	v_mfma_f32_16x16x32_bf16 v[90:93], v[154:157], v[194:197], v[90:93]
	v_mfma_f32_16x16x32_bf16 v[78:81], v[146:149], v[202:205], v[78:81]
	v_mfma_f32_16x16x32_bf16 v[74:77], v[154:157], v[202:205], v[74:77]
	v_mfma_f32_16x16x32_bf16 v[126:129], v[150:153], v[182:185], v[126:129]
	v_mfma_f32_16x16x32_bf16 v[122:125], v[158:161], v[182:185], v[122:125]
	v_mfma_f32_16x16x32_bf16 v[110:113], v[150:153], v[190:193], v[110:113]
	v_mfma_f32_16x16x32_bf16 v[106:109], v[158:161], v[190:193], v[106:109]
	v_mfma_f32_16x16x32_bf16 v[94:97], v[150:153], v[198:201], v[94:97]
	v_mfma_f32_16x16x32_bf16 v[90:93], v[158:161], v[198:201], v[90:93]
	v_mfma_f32_16x16x32_bf16 v[78:81], v[150:153], v[222:225], v[78:81]
	v_mfma_f32_16x16x32_bf16 v[74:77], v[158:161], v[222:225], v[74:77]
	s_setprio 0
	s_setprio 1
	v_mfma_f32_16x16x32_bf16 v[118:121], v[162:165], v[178:181], v[118:121]
	v_mfma_f32_16x16x32_bf16 v[114:117], v[170:173], v[178:181], v[114:117]
	v_mfma_f32_16x16x32_bf16 v[102:105], v[162:165], v[186:189], v[102:105]
	v_mfma_f32_16x16x32_bf16 v[98:101], v[170:173], v[186:189], v[98:101]
	v_mfma_f32_16x16x32_bf16 v[86:89], v[162:165], v[194:197], v[86:89]
	v_mfma_f32_16x16x32_bf16 v[82:85], v[170:173], v[194:197], v[82:85]
	v_mfma_f32_16x16x32_bf16 v[70:73], v[162:165], v[202:205], v[70:73]
	v_mfma_f32_16x16x32_bf16 v[66:69], v[170:173], v[202:205], v[66:69]
	v_mfma_f32_16x16x32_bf16 v[118:121], v[166:169], v[182:185], v[118:121]
	v_mfma_f32_16x16x32_bf16 v[114:117], v[174:177], v[182:185], v[114:117]
	v_mfma_f32_16x16x32_bf16 v[102:105], v[166:169], v[190:193], v[102:105]
	v_mfma_f32_16x16x32_bf16 v[98:101], v[174:177], v[190:193], v[98:101]
	v_mfma_f32_16x16x32_bf16 v[86:89], v[166:169], v[198:201], v[86:89]
	v_mfma_f32_16x16x32_bf16 v[82:85], v[174:177], v[198:201], v[82:85]
	v_mfma_f32_16x16x32_bf16 v[70:73], v[166:169], v[222:225], v[70:73]
	v_mfma_f32_16x16x32_bf16 v[66:69], v[174:177], v[222:225], v[66:69]
	s_barrier
	s_setprio 0
	s_add_i32 s18, s47, s24
	v_lshl_add_u64 v[142:143], s[20:21], 0, v[130:131]
	s_mov_b32 m0, s18
	ds_read_b128 v[178:181], v144 offset:16384
	ds_read_b128 v[182:185], v144 offset:17408
	ds_read_b128 v[186:189], v144 offset:18432
	ds_read_b128 v[190:193], v144 offset:19456
	ds_read_b128 v[194:197], v144 offset:20480
	ds_read_b128 v[198:201], v144 offset:21504
	ds_read_b128 v[202:205], v144 offset:22528
	ds_read_b128 v[222:225], v144 offset:23552
	global_load_lds_dwordx4 v[142:143], off
	s_add_i32 m0, s18, 0x2000
	s_add_u32 s18, s20, 0xb0000
	v_lshl_add_u64 v[206:207], s[20:21], 0, v[132:133]
	s_addc_u32 s19, s21, 0
	s_add_i32 s47, s48, s24
	global_load_lds_dwordx4 v[206:207], off
	v_lshl_add_u64 v[218:219], s[18:19], 0, v[130:131]
	s_mov_b32 m0, s47
	v_lshl_add_u64 v[226:227], s[22:23], 0, v[132:133]
	global_load_lds_dwordx4 v[218:219], off
	v_lshl_add_u64 v[218:219], s[18:19], 0, v[132:133]
	s_add_i32 m0, s47, 0x2000
	s_nop 0
	global_load_lds_dwordx4 v[218:219], off
	v_lshl_add_u64 v[218:219], s[22:23], 0, v[130:131]
	s_mov_b32 m0, s25
	s_nop 0
	global_load_lds_dwordx4 v[218:219], off
	s_mov_b32 m0, s26
	s_nop 0
	global_load_lds_dwordx4 v[226:227], off
	s_waitcnt vmcnt(8)
	s_waitcnt lgkmcnt(0)
	s_setprio 1
	s_barrier
	s_waitcnt lgkmcnt(0)
	v_mfma_f32_16x16x32_bf16 v[62:65], v[146:149], v[178:181], v[62:65]
	v_mfma_f32_16x16x32_bf16 v[58:61], v[154:157], v[178:181], v[58:61]
	v_mfma_f32_16x16x32_bf16 v[46:49], v[146:149], v[186:189], v[46:49]
	v_mfma_f32_16x16x32_bf16 v[42:45], v[154:157], v[186:189], v[42:45]
	v_mfma_f32_16x16x32_bf16 v[30:33], v[146:149], v[194:197], v[30:33]
	v_mfma_f32_16x16x32_bf16 v[26:29], v[154:157], v[194:197], v[26:29]
	v_mfma_f32_16x16x32_bf16 v[14:17], v[146:149], v[202:205], v[14:17]
	v_mfma_f32_16x16x32_bf16 v[10:13], v[154:157], v[202:205], v[10:13]
	v_mfma_f32_16x16x32_bf16 v[62:65], v[150:153], v[182:185], v[62:65]
	v_mfma_f32_16x16x32_bf16 v[58:61], v[158:161], v[182:185], v[58:61]
	v_mfma_f32_16x16x32_bf16 v[46:49], v[150:153], v[190:193], v[46:49]
	v_mfma_f32_16x16x32_bf16 v[42:45], v[158:161], v[190:193], v[42:45]
	v_mfma_f32_16x16x32_bf16 v[30:33], v[150:153], v[198:201], v[30:33]
	v_mfma_f32_16x16x32_bf16 v[26:29], v[158:161], v[198:201], v[26:29]
	v_mfma_f32_16x16x32_bf16 v[14:17], v[150:153], v[222:225], v[14:17]
	v_mfma_f32_16x16x32_bf16 v[10:13], v[158:161], v[222:225], v[10:13]
	s_setprio 0
	s_setprio 1
	v_mfma_f32_16x16x32_bf16 v[54:57], v[162:165], v[178:181], v[54:57]
	v_mfma_f32_16x16x32_bf16 v[50:53], v[170:173], v[178:181], v[50:53]
	v_mfma_f32_16x16x32_bf16 v[38:41], v[162:165], v[186:189], v[38:41]
	v_mfma_f32_16x16x32_bf16 v[34:37], v[170:173], v[186:189], v[34:37]
	v_mfma_f32_16x16x32_bf16 v[22:25], v[162:165], v[194:197], v[22:25]
	v_mfma_f32_16x16x32_bf16 v[18:21], v[170:173], v[194:197], v[18:21]
	v_mfma_f32_16x16x32_bf16 v[6:9], v[162:165], v[202:205], v[6:9]
	v_mfma_f32_16x16x32_bf16 v[2:5], v[170:173], v[202:205], v[2:5]
	v_mfma_f32_16x16x32_bf16 v[54:57], v[166:169], v[182:185], v[54:57]
	v_mfma_f32_16x16x32_bf16 v[50:53], v[174:177], v[182:185], v[50:53]
	v_mfma_f32_16x16x32_bf16 v[38:41], v[166:169], v[190:193], v[38:41]
	v_mfma_f32_16x16x32_bf16 v[34:37], v[174:177], v[190:193], v[34:37]
	v_mfma_f32_16x16x32_bf16 v[22:25], v[166:169], v[198:201], v[22:25]
	v_mfma_f32_16x16x32_bf16 v[18:21], v[174:177], v[198:201], v[18:21]
	v_mfma_f32_16x16x32_bf16 v[6:9], v[166:169], v[222:225], v[6:9]
	v_mfma_f32_16x16x32_bf16 v[2:5], v[174:177], v[222:225], v[2:5]
	s_barrier
	s_setprio 0
	s_add_i32 s47, 0, 0x18000
	v_add_u32_e32 v0, s47, v135
	s_add_i32 s48, 0, 0x1c000
	ds_read_b128 v[146:149], v0
	ds_read_b128 v[150:153], v0 offset:1024
	ds_read_b128 v[154:157], v0 offset:2048
	ds_read_b128 v[158:161], v0 offset:3072
	v_add_u32_e32 v0, s48, v135
	ds_read_b128 v[162:165], v0
	ds_read_b128 v[166:169], v0 offset:1024
	ds_read_b128 v[170:173], v0 offset:2048
	ds_read_b128 v[174:177], v0 offset:3072
	s_add_u32 s18, s22, 0xb0000
	s_addc_u32 s19, s23, 0
	s_mov_b32 m0, s27
	v_lshl_add_u64 v[228:229], s[18:19], 0, v[130:131]
	ds_read_b128 v[178:181], v144 offset:32768
	ds_read_b128 v[182:185], v144 offset:33792
	ds_read_b128 v[186:189], v144 offset:34816
	ds_read_b128 v[190:193], v144 offset:35840
	ds_read_b128 v[194:197], v144 offset:36864
	ds_read_b128 v[198:201], v144 offset:37888
	ds_read_b128 v[202:205], v144 offset:38912
	ds_read_b128 v[222:225], v144 offset:39936
	global_load_lds_dwordx4 v[228:229], off
	v_lshl_add_u64 v[228:229], s[18:19], 0, v[132:133]
	s_mov_b32 m0, s28
	s_nop 0
	global_load_lds_dwordx4 v[228:229], off
	s_waitcnt vmcnt(8)
	s_waitcnt lgkmcnt(0)
	s_setprio 1
	s_barrier
	s_waitcnt lgkmcnt(0)
	v_mfma_f32_16x16x32_bf16 v[126:129], v[146:149], v[178:181], v[126:129]
	v_mfma_f32_16x16x32_bf16 v[122:125], v[154:157], v[178:181], v[122:125]
	v_mfma_f32_16x16x32_bf16 v[110:113], v[146:149], v[186:189], v[110:113]
	v_mfma_f32_16x16x32_bf16 v[106:109], v[154:157], v[186:189], v[106:109]
	v_mfma_f32_16x16x32_bf16 v[94:97], v[146:149], v[194:197], v[94:97]
	v_mfma_f32_16x16x32_bf16 v[90:93], v[154:157], v[194:197], v[90:93]
	v_mfma_f32_16x16x32_bf16 v[78:81], v[146:149], v[202:205], v[78:81]
	v_mfma_f32_16x16x32_bf16 v[74:77], v[154:157], v[202:205], v[74:77]
	v_mfma_f32_16x16x32_bf16 v[126:129], v[150:153], v[182:185], v[126:129]
	v_mfma_f32_16x16x32_bf16 v[122:125], v[158:161], v[182:185], v[122:125]
	v_mfma_f32_16x16x32_bf16 v[110:113], v[150:153], v[190:193], v[110:113]
	v_mfma_f32_16x16x32_bf16 v[106:109], v[158:161], v[190:193], v[106:109]
	v_mfma_f32_16x16x32_bf16 v[94:97], v[150:153], v[198:201], v[94:97]
	v_mfma_f32_16x16x32_bf16 v[90:93], v[158:161], v[198:201], v[90:93]
	v_mfma_f32_16x16x32_bf16 v[78:81], v[150:153], v[222:225], v[78:81]
	v_mfma_f32_16x16x32_bf16 v[74:77], v[158:161], v[222:225], v[74:77]
	s_setprio 0
	s_setprio 1
	v_mfma_f32_16x16x32_bf16 v[118:121], v[162:165], v[178:181], v[118:121]
	v_mfma_f32_16x16x32_bf16 v[114:117], v[170:173], v[178:181], v[114:117]
	v_mfma_f32_16x16x32_bf16 v[102:105], v[162:165], v[186:189], v[102:105]
	v_mfma_f32_16x16x32_bf16 v[98:101], v[170:173], v[186:189], v[98:101]
	v_mfma_f32_16x16x32_bf16 v[86:89], v[162:165], v[194:197], v[86:89]
	v_mfma_f32_16x16x32_bf16 v[82:85], v[170:173], v[194:197], v[82:85]
	v_mfma_f32_16x16x32_bf16 v[70:73], v[162:165], v[202:205], v[70:73]
	v_mfma_f32_16x16x32_bf16 v[66:69], v[170:173], v[202:205], v[66:69]
	v_mfma_f32_16x16x32_bf16 v[118:121], v[166:169], v[182:185], v[118:121]
	v_mfma_f32_16x16x32_bf16 v[114:117], v[174:177], v[182:185], v[114:117]
	v_mfma_f32_16x16x32_bf16 v[102:105], v[166:169], v[190:193], v[102:105]
	v_mfma_f32_16x16x32_bf16 v[98:101], v[174:177], v[190:193], v[98:101]
	v_mfma_f32_16x16x32_bf16 v[86:89], v[166:169], v[198:201], v[86:89]
	v_mfma_f32_16x16x32_bf16 v[82:85], v[174:177], v[198:201], v[82:85]
	v_mfma_f32_16x16x32_bf16 v[70:73], v[166:169], v[222:225], v[70:73]
	v_mfma_f32_16x16x32_bf16 v[66:69], v[174:177], v[222:225], v[66:69]
	s_barrier
	s_setprio 0
	s_add_i32 s18, s47, s24
	v_lshl_add_u64 v[142:143], v[142:143], 0, s[44:45]
	s_mov_b32 m0, s18
	ds_read_b128 v[178:181], v144 offset:49152
	ds_read_b128 v[182:185], v144 offset:50176
	ds_read_b128 v[186:189], v144 offset:51200
	ds_read_b128 v[190:193], v144 offset:52224
	ds_read_b128 v[194:197], v144 offset:53248
	ds_read_b128 v[198:201], v144 offset:54272
	ds_read_b128 v[202:205], v144 offset:55296
	ds_read_b128 v[222:225], v144 offset:56320
	global_load_lds_dwordx4 v[142:143], off
	s_add_i32 m0, s18, 0x2000
	s_add_u32 s18, s20, 0xb0080
	v_lshl_add_u64 v[142:143], v[206:207], 0, s[44:45]
	s_addc_u32 s19, s21, 0
	s_add_i32 s20, s48, s24
	global_load_lds_dwordx4 v[142:143], off
	v_lshl_add_u64 v[142:143], s[18:19], 0, v[130:131]
	s_mov_b32 m0, s20
	s_nop 0
	global_load_lds_dwordx4 v[142:143], off
	v_lshl_add_u64 v[142:143], s[18:19], 0, v[132:133]
	s_add_i32 m0, s20, 0x2000
	s_nop 0
	global_load_lds_dwordx4 v[142:143], off
	v_lshl_add_u64 v[142:143], v[218:219], 0, s[44:45]
	s_mov_b32 m0, s31
	s_nop 0
	global_load_lds_dwordx4 v[142:143], off
	v_lshl_add_u64 v[142:143], v[226:227], 0, s[44:45]
	s_mov_b32 m0, s33
	s_nop 0
	global_load_lds_dwordx4 v[142:143], off
	s_waitcnt vmcnt(8)
	s_waitcnt lgkmcnt(0)
	s_setprio 1
	s_barrier
	s_waitcnt lgkmcnt(0)
	v_mfma_f32_16x16x32_bf16 v[62:65], v[146:149], v[178:181], v[62:65]
	v_mfma_f32_16x16x32_bf16 v[58:61], v[154:157], v[178:181], v[58:61]
	v_mfma_f32_16x16x32_bf16 v[46:49], v[146:149], v[186:189], v[46:49]
	v_mfma_f32_16x16x32_bf16 v[42:45], v[154:157], v[186:189], v[42:45]
	v_mfma_f32_16x16x32_bf16 v[30:33], v[146:149], v[194:197], v[30:33]
	v_mfma_f32_16x16x32_bf16 v[26:29], v[154:157], v[194:197], v[26:29]
	v_mfma_f32_16x16x32_bf16 v[14:17], v[146:149], v[202:205], v[14:17]
	v_mfma_f32_16x16x32_bf16 v[10:13], v[154:157], v[202:205], v[10:13]
	v_mfma_f32_16x16x32_bf16 v[62:65], v[150:153], v[182:185], v[62:65]
	v_mfma_f32_16x16x32_bf16 v[58:61], v[158:161], v[182:185], v[58:61]
	v_mfma_f32_16x16x32_bf16 v[46:49], v[150:153], v[190:193], v[46:49]
	v_mfma_f32_16x16x32_bf16 v[42:45], v[158:161], v[190:193], v[42:45]
	v_mfma_f32_16x16x32_bf16 v[30:33], v[150:153], v[198:201], v[30:33]
	v_mfma_f32_16x16x32_bf16 v[26:29], v[158:161], v[198:201], v[26:29]
	v_mfma_f32_16x16x32_bf16 v[14:17], v[150:153], v[222:225], v[14:17]
	v_mfma_f32_16x16x32_bf16 v[10:13], v[158:161], v[222:225], v[10:13]
	s_setprio 0
	s_setprio 1
	v_mfma_f32_16x16x32_bf16 v[54:57], v[162:165], v[178:181], v[54:57]
	v_mfma_f32_16x16x32_bf16 v[50:53], v[170:173], v[178:181], v[50:53]
	v_mfma_f32_16x16x32_bf16 v[38:41], v[162:165], v[186:189], v[38:41]
	v_mfma_f32_16x16x32_bf16 v[34:37], v[170:173], v[186:189], v[34:37]
	v_mfma_f32_16x16x32_bf16 v[22:25], v[162:165], v[194:197], v[22:25]
	v_mfma_f32_16x16x32_bf16 v[18:21], v[170:173], v[194:197], v[18:21]
	v_mfma_f32_16x16x32_bf16 v[6:9], v[162:165], v[202:205], v[6:9]
	v_mfma_f32_16x16x32_bf16 v[2:5], v[170:173], v[202:205], v[2:5]
	v_mfma_f32_16x16x32_bf16 v[54:57], v[166:169], v[182:185], v[54:57]
	v_mfma_f32_16x16x32_bf16 v[50:53], v[174:177], v[182:185], v[50:53]
	v_mfma_f32_16x16x32_bf16 v[38:41], v[166:169], v[190:193], v[38:41]
	v_mfma_f32_16x16x32_bf16 v[34:37], v[174:177], v[190:193], v[34:37]
	v_mfma_f32_16x16x32_bf16 v[22:25], v[166:169], v[198:201], v[22:25]
	v_mfma_f32_16x16x32_bf16 v[18:21], v[174:177], v[198:201], v[18:21]
	v_mfma_f32_16x16x32_bf16 v[6:9], v[166:169], v[222:225], v[6:9]
	v_mfma_f32_16x16x32_bf16 v[2:5], v[174:177], v[222:225], v[2:5]
	s_barrier
	s_setprio 0
	s_add_i32 s46, s46, 2
	s_add_u32 s17, s17, 0x100
	s_addc_u32 s42, s42, 0
	s_cmp_gt_u32 s46, 41
	s_mov_b64 s[18:19], s[2:3]
	s_cbranch_scc0 .LBB0_849
	s_and_b64 vcc, exec, s[12:13]
	s_cbranch_vccz .LBB0_852
	s_barrier
